# attention: each CU runs its long causal half first (keeps the 16 CUs sharing a head's K/V in step for L2 reuse)
# speedup vs baseline: 1.0037x; 1.0037x over previous
; template <int MODE> __device__ __forceinline__ void attn_phase(LAS unsigned char* lds, const bf16_t* Q, const bf16_t* KF, const bf16_t* VT, bf16_t* O, const int* positions, const float* gq, int G, int bid) {
;     ...
;     for (int it = bid; it < 1024; it += G) {
;         const int bh = it >> 4, pp = it & 15, b = bh >> 3, h = bh & 7;
;         for (int half = 0; half < 2; ++half) {
;             const int j = half ? 31 - pp : pp;
;             const int ntiles = 4 * j + 4, my_last = 4 * j + (w >> 1);
;             const size_t qrow = (size_t)b * SEQ + 256 * j + 32 * w + lq;
.LBB0_664:
	s_ashr_i32 s4, s48, 7
	s_and_b32 s50, s48, 15
	s_ashr_i32 s5, s4, 31
	s_bfe_u32 s10, s48, 0x30004
	s_xor_b32 s49, s50, 31
	s_lshl_b64 s[26:27], s[4:5], 13
	s_lshl_b64 s[6:7], s[4:5], 14
	s_add_u32 s5, s33, s6
	s_addc_u32 s6, s35, s7
	s_mul_hi_i32 s7, s4, 0x1800000
	s_mul_i32 s4, s4, 0x1800000
	s_add_u32 s4, s3, s4
	s_mul_i32 s22, s10, 0x180
	s_addc_u32 s7, s29, s7
	s_add_u32 s12, s4, s22
	s_addc_u32 s4, s7, 0
	s_lshl_b32 s7, s10, 24
	s_add_u32 s16, s5, s7
	v_lshl_add_u64 v[212:213], v[206:207], 0, s[22:23]
	s_addc_u32 s5, s6, 0
	s_lshl_b32 s22, s10, 8
	s_and_b32 s13, s4, 0xffff
	s_and_b32 s17, s5, 0xffff
	v_lshl_add_u64 v[214:215], v[210:211], 0, s[22:23]
	s_mov_b64 s[10:11], -1
	s_branch .LBB0_667
